# store-carry counted waits across the in_proj unit seam: no vmcnt(0) drain at unit start, first two waits of the first K-trip count the epilogue stores
# speedup vs baseline: 1.0005x; 1.0005x over previous
.LBB0_308:
	s_and_b32 s34, s12, 3
	s_add_i32 m0, s96, 0x18000
	v_lshl_add_u64 v[6:7], v[6:7], 0, s[68:69]
	s_lshl_b32 s42, s13, 6
	s_lshl_b32 s12, s13, 13
	s_lshl_b32 s35, s34, 12
	s_waitcnt vmcnt(2)
	s_barrier
	global_load_lds_dwordx4 v[6:7], off
	v_lshl_add_u64 v[4:5], v[4:5], 0, s[68:69]
	s_add_i32 m0, s96, 0x1a000
	s_add_i32 s43, s96, 0x8000
	s_add_i32 s83, s96, 0xa000
	global_load_lds_dwordx4 v[4:5], off
	v_lshl_add_u64 v[0:1], v[0:1], 0, s[68:69]
	s_mov_b32 m0, s43
	s_add_u32 s6, s8, 0x40080
	global_load_lds_dwordx4 v[0:1], off
	v_lshl_add_u64 v[0:1], v[2:3], 0, s[68:69]
	s_mov_b32 m0, s83
	s_addc_u32 s7, s9, 0
	global_load_lds_dwordx4 v[0:1], off
	s_add_i32 m0, s96, 0x1c000
	v_lshl_add_u64 v[0:1], s[6:7], 0, v[182:183]
	global_load_lds_dwordx4 v[0:1], off
	v_lshl_add_u64 v[0:1], s[6:7], 0, v[34:35]
	s_add_i32 m0, s96, 0x1e000
	s_cmpk_lt_u32 s0, 0x100
	global_load_lds_dwordx4 v[0:1], off
	v_bfe_u32 v1, v8, 4, 2
	v_and_b32_e32 v204, 15, v8
	v_lshlrev_b32_e32 v0, 4, v1
	v_lshlrev_b32_e32 v3, 2, v8
	s_cselect_b64 s[52:53], -1, 0
	s_bitcmp0_b32 s0, 6
	v_lshl_or_b32 v2, v204, 6, v0
	v_and_b32_e32 v3, 32, v3
	s_cselect_b64 s[6:7], -1, 0
	s_lshl_b32 s0, s13, 2
	v_bitop3_b32 v4, v2, s12, v3 bitop3:0xde
	s_or_b32 s12, s0, s34
	s_ashr_i32 s13, s12, 31
	s_lshl_b64 s[12:13], s[12:13], 13
	v_bitop3_b32 v205, v2, s35, v3 bitop3:0xde
	v_lshlrev_b32_e32 v2, 4, v204
	s_add_u32 s12, s54, s12
	v_lshl_or_b32 v32, v1, 8, v2
	s_addc_u32 s13, s87, s13
	v_lshl_add_u64 v[190:191], s[12:13], 0, v[32:33]
	v_readlane_b32 s12, v253, 33
	s_waitcnt vmcnt(6)
	v_writelane_b32 v254, s54, 46
	v_readlane_b32 s13, v253, 34
	v_lshl_or_b32 v2, s34, 6, v0
	v_mov_b32_e32 v3, v33
	v_writelane_b32 v254, s87, 47
	v_mov_b32_e32 v1, v33
	s_mov_b32 s87, s12
	v_readlane_b32 s12, v253, 37
	s_mov_b32 s82, 0
	v_or_b32_e32 v206, 16, v204
	v_or_b32_e32 v207, 32, v204
	v_or_b32_e32 v208, 48, v204
	v_lshl_add_u64 v[188:189], s[24:25], 0, v[2:3]
	v_lshl_add_u64 v[192:193], s[30:31], 0, v[0:1]
	v_lshl_add_u64 v[194:195], s[36:37], 0, v[0:1]
	v_add_u32_e32 v209, 0, v4
	s_mov_b32 s88, s12
	s_barrier
	v_readlane_b32 s13, v253, 38
	s_mov_b32 s100, 0
	s_branch .LBB0_311

.LBB0_310:
	s_andn2_b64 vcc, exec, s[8:9]
	s_cmp_lt_u32 s87, 16
	s_cselect_b32 s100, 16, 8
	s_mov_b32 s87, s62
	s_mov_b32 s88, s56
	s_mov_b64 s[8:9], s[72:73]
	s_mov_b64 s[10:11], s[70:71]
	s_cbranch_vccz .LBB0_369

.Lpeel_a:
	s_mov_b64 s[34:35], -1
	s_or_b32 s92, s89, 1
	s_lshl_b64 s[76:77], s[92:93], 7
	s_add_u32 s0, s10, s76
	s_addc_u32 s54, s11, s77
	s_add_i32 s92, s89, 2
	s_lshl_b64 s[78:79], s[92:93], 7
	s_add_u32 s80, s10, s78
	s_addc_u32 s81, s11, s79
	s_and_b64 s[76:77], s[34:35], exec
	s_cselect_b32 s77, s81, s57
	s_cselect_b32 s76, s80, s66
	s_add_u32 s78, s8, s78
	s_addc_u32 s79, s9, s79
	s_and_b64 s[34:35], s[34:35], exec
	s_cselect_b32 s35, s79, s63
	s_cselect_b32 s34, s78, s90
	s_add_i32 s80, 0, 0x10000
	s_add_i32 s81, 0, 0x14000
	v_add_u32_e32 v12, s80, v205
	v_add_u32_e32 v28, s81, v205
	ds_read_b128 v[0:3], v12
	ds_read_b128 v[4:7], v12 offset:1024
	ds_read_b128 v[8:11], v12 offset:2048
	ds_read_b128 v[12:15], v12 offset:3072
	ds_read_b128 v[16:19], v28
	ds_read_b128 v[20:23], v28 offset:1024
	ds_read_b128 v[24:27], v28 offset:2048
	ds_read_b128 v[28:31], v28 offset:3072
	s_add_u32 s78, s0, 0x40000
	s_addc_u32 s79, s54, 0
	v_lshl_add_u64 v[202:203], s[78:79], 0, v[184:185]
	s_add_i32 m0, s96, 0xc000
	ds_read_b128 v[166:169], v209
	ds_read_b128 v[170:173], v209 offset:1024
	ds_read_b128 v[174:177], v209 offset:2048
	ds_read_b128 v[178:181], v209 offset:3072
	ds_read_b128 v[196:199], v209 offset:4096
	ds_read_b128 v[210:213], v209 offset:5120
	ds_read_b128 v[244:247], v209 offset:6144
	ds_read_b128 v[248:251], v209 offset:7168
	global_load_lds_dwordx4 v[202:203], off
	v_lshl_add_u64 v[202:203], s[78:79], 0, v[186:187]
	s_add_i32 m0, s96, 0xe000
	s_nop 0
	global_load_lds_dwordx4 v[202:203], off
	s_cmp_eq_u32 s100, 16
	s_cbranch_scc1 .Lw16_a0
	s_cmp_eq_u32 s100, 8
	s_cbranch_scc1 .Lw8_a0
	s_waitcnt vmcnt(8)
	s_branch .Lwd_a0
.Lw16_a0:
	s_waitcnt vmcnt(24)
	s_branch .Lwd_a0
.Lw8_a0:
	s_waitcnt vmcnt(16)
.Lwd_a0:
	s_waitcnt lgkmcnt(0)
	s_barrier
	s_setprio 1
	s_waitcnt lgkmcnt(0)
	v_mfma_f32_16x16x32_bf16 v[162:165], v[0:3], v[166:169], 0
	v_mfma_f32_16x16x32_bf16 v[158:161], v[8:11], v[166:169], 0
	v_mfma_f32_16x16x32_bf16 v[146:149], v[0:3], v[174:177], 0
	v_mfma_f32_16x16x32_bf16 v[142:145], v[8:11], v[174:177], 0
	v_mfma_f32_16x16x32_bf16 v[130:133], v[0:3], v[196:199], 0
	v_mfma_f32_16x16x32_bf16 v[126:129], v[8:11], v[196:199], 0
	v_mfma_f32_16x16x32_bf16 v[114:117], v[0:3], v[244:247], 0
	v_mfma_f32_16x16x32_bf16 v[110:113], v[8:11], v[244:247], 0
	v_mfma_f32_16x16x32_bf16 v[162:165], v[4:7], v[170:173], v[162:165]
	v_mfma_f32_16x16x32_bf16 v[158:161], v[12:15], v[170:173], v[158:161]
	v_mfma_f32_16x16x32_bf16 v[146:149], v[4:7], v[178:181], v[146:149]
	v_mfma_f32_16x16x32_bf16 v[142:145], v[12:15], v[178:181], v[142:145]
	v_mfma_f32_16x16x32_bf16 v[130:133], v[4:7], v[210:213], v[130:133]
	v_mfma_f32_16x16x32_bf16 v[126:129], v[12:15], v[210:213], v[126:129]
	v_mfma_f32_16x16x32_bf16 v[114:117], v[4:7], v[248:251], v[114:117]
	v_mfma_f32_16x16x32_bf16 v[110:113], v[12:15], v[248:251], v[110:113]
	s_setprio 0
	s_setprio 1
	v_mfma_f32_16x16x32_bf16 v[154:157], v[16:19], v[166:169], 0
	v_mfma_f32_16x16x32_bf16 v[150:153], v[24:27], v[166:169], 0
	v_mfma_f32_16x16x32_bf16 v[138:141], v[16:19], v[174:177], 0
	v_mfma_f32_16x16x32_bf16 v[134:137], v[24:27], v[174:177], 0
	v_mfma_f32_16x16x32_bf16 v[122:125], v[16:19], v[196:199], 0
	v_mfma_f32_16x16x32_bf16 v[118:121], v[24:27], v[196:199], 0
	v_mfma_f32_16x16x32_bf16 v[106:109], v[16:19], v[244:247], 0
	v_mfma_f32_16x16x32_bf16 v[102:105], v[24:27], v[244:247], 0
	v_mfma_f32_16x16x32_bf16 v[154:157], v[20:23], v[170:173], v[154:157]
	v_mfma_f32_16x16x32_bf16 v[150:153], v[28:31], v[170:173], v[150:153]
	v_mfma_f32_16x16x32_bf16 v[138:141], v[20:23], v[178:181], v[138:141]
	v_mfma_f32_16x16x32_bf16 v[134:137], v[28:31], v[178:181], v[134:137]
	v_mfma_f32_16x16x32_bf16 v[122:125], v[20:23], v[210:213], v[122:125]
	v_mfma_f32_16x16x32_bf16 v[118:121], v[28:31], v[210:213], v[118:121]
	v_mfma_f32_16x16x32_bf16 v[106:109], v[20:23], v[248:251], v[106:109]
	v_mfma_f32_16x16x32_bf16 v[102:105], v[28:31], v[248:251], v[102:105]
	s_setprio 0
	s_barrier
	s_add_i32 s0, s80, s95
	v_lshl_add_u64 v[202:203], s[34:35], 0, v[182:183]
	s_mov_b32 m0, s0
	ds_read_b128 v[166:169], v209 offset:16384
	ds_read_b128 v[170:173], v209 offset:17408
	ds_read_b128 v[174:177], v209 offset:18432
	ds_read_b128 v[178:181], v209 offset:19456
	ds_read_b128 v[196:199], v209 offset:20480
	ds_read_b128 v[210:213], v209 offset:21504
	ds_read_b128 v[244:247], v209 offset:22528
	ds_read_b128 v[248:251], v209 offset:23552
	global_load_lds_dwordx4 v[202:203], off
	s_add_i32 m0, s0, 0x2000
	s_add_u32 s78, s34, 0x40000
	v_lshl_add_u64 v[214:215], s[34:35], 0, v[34:35]
	s_addc_u32 s79, s35, 0
	s_add_i32 s0, s81, s95
	global_load_lds_dwordx4 v[214:215], off
	v_lshl_add_u64 v[218:219], s[78:79], 0, v[182:183]
	s_mov_b32 m0, s0
	v_lshl_add_u64 v[222:223], s[76:77], 0, v[184:185]
	global_load_lds_dwordx4 v[218:219], off
	v_lshl_add_u64 v[218:219], s[78:79], 0, v[34:35]
	s_add_i32 m0, s0, 0x2000
	v_lshl_add_u64 v[236:237], s[76:77], 0, v[186:187]
	global_load_lds_dwordx4 v[218:219], off
	s_mov_b32 m0, s96
	s_nop 0
	global_load_lds_dwordx4 v[222:223], off
	s_mov_b32 m0, s97
	s_nop 0
	global_load_lds_dwordx4 v[236:237], off
	s_cmp_eq_u32 s100, 16
	s_cbranch_scc1 .Lw16_a1
	s_cmp_eq_u32 s100, 8
	s_cbranch_scc1 .Lw8_a1
	s_waitcnt vmcnt(8)
	s_branch .Lwd_a1

.Lwd_a1:
	s_waitcnt lgkmcnt(0)
	s_barrier
	s_setprio 1
	s_waitcnt lgkmcnt(0)
	v_mfma_f32_16x16x32_bf16 v[98:101], v[0:3], v[166:169], 0
	v_mfma_f32_16x16x32_bf16 v[94:97], v[8:11], v[166:169], 0
	v_mfma_f32_16x16x32_bf16 v[82:85], v[0:3], v[174:177], 0
	v_mfma_f32_16x16x32_bf16 v[78:81], v[8:11], v[174:177], 0
	v_mfma_f32_16x16x32_bf16 v[66:69], v[0:3], v[196:199], 0
	v_mfma_f32_16x16x32_bf16 v[62:65], v[8:11], v[196:199], 0
	v_mfma_f32_16x16x32_bf16 v[0:3], v[0:3], v[244:247], 0
	v_mfma_f32_16x16x32_bf16 v[98:101], v[4:7], v[170:173], v[98:101]
	v_mfma_f32_16x16x32_bf16 v[94:97], v[12:15], v[170:173], v[94:97]
	v_mfma_f32_16x16x32_bf16 v[82:85], v[4:7], v[178:181], v[82:85]
	v_mfma_f32_16x16x32_bf16 v[78:81], v[12:15], v[178:181], v[78:81]
	v_mfma_f32_16x16x32_bf16 v[66:69], v[4:7], v[210:213], v[66:69]
	v_mfma_f32_16x16x32_bf16 v[62:65], v[12:15], v[210:213], v[62:65]
	v_mfma_f32_16x16x32_bf16 v[0:3], v[4:7], v[248:251], v[0:3]
	v_mfma_f32_16x16x32_bf16 v[4:7], v[8:11], v[244:247], 0
	v_mfma_f32_16x16x32_bf16 v[4:7], v[12:15], v[248:251], v[4:7]
	s_setprio 0
	s_setprio 1
	v_mfma_f32_16x16x32_bf16 v[46:49], v[16:19], v[174:177], 0
	v_mfma_f32_16x16x32_bf16 v[74:77], v[20:23], v[178:181], v[46:49]
	v_mfma_f32_16x16x32_bf16 v[46:49], v[24:27], v[174:177], 0
	v_mfma_f32_16x16x32_bf16 v[70:73], v[28:31], v[178:181], v[46:49]
	v_mfma_f32_16x16x32_bf16 v[46:49], v[16:19], v[196:199], 0
	v_mfma_f32_16x16x32_bf16 v[8:11], v[16:19], v[166:169], 0
	v_mfma_f32_16x16x32_bf16 v[58:61], v[20:23], v[210:213], v[46:49]
	v_mfma_f32_16x16x32_bf16 v[46:49], v[24:27], v[196:199], 0
	v_mfma_f32_16x16x32_bf16 v[16:19], v[16:19], v[244:247], 0
	v_mfma_f32_16x16x32_bf16 v[8:11], v[20:23], v[170:173], v[8:11]
	v_mfma_f32_16x16x32_bf16 v[12:15], v[24:27], v[166:169], 0
	v_mfma_f32_16x16x32_bf16 v[54:57], v[28:31], v[210:213], v[46:49]
	v_mfma_f32_16x16x32_bf16 v[16:19], v[20:23], v[248:251], v[16:19]
	v_mfma_f32_16x16x32_bf16 v[20:23], v[24:27], v[244:247], 0
	v_mfma_f32_16x16x32_bf16 v[12:15], v[28:31], v[170:173], v[12:15]
	v_mfma_f32_16x16x32_bf16 v[20:23], v[28:31], v[248:251], v[20:23]
	s_setprio 0
	s_barrier
	s_add_i32 s0, 0, 0x18000
	v_add_u32_e32 v32, s0, v205
	s_add_i32 s54, 0, 0x1c000
	ds_read_b128 v[24:27], v32
	ds_read_b128 v[28:31], v32 offset:1024
	ds_read_b128 v[38:41], v32 offset:2048
	ds_read_b128 v[42:45], v32 offset:3072
	v_add_u32_e32 v32, s54, v205
	ds_read_b128 v[166:169], v32
	ds_read_b128 v[170:173], v32 offset:1024
	ds_read_b128 v[174:177], v32 offset:2048
	ds_read_b128 v[178:181], v32 offset:3072
	s_add_u32 s76, s76, 0x40000
	s_addc_u32 s77, s77, 0
	s_mov_b32 m0, s40
	v_lshl_add_u64 v[218:219], s[76:77], 0, v[184:185]
	ds_read_b128 v[46:49], v209 offset:32768
	ds_read_b128 v[50:53], v209 offset:33792
	ds_read_b128 v[86:89], v209 offset:34816
	ds_read_b128 v[90:93], v209 offset:35840
	ds_read_b128 v[196:199], v209 offset:36864
	ds_read_b128 v[210:213], v209 offset:37888
	ds_read_b128 v[244:247], v209 offset:38912
	ds_read_b128 v[248:251], v209 offset:39936
	global_load_lds_dwordx4 v[218:219], off
	v_lshl_add_u64 v[218:219], s[76:77], 0, v[186:187]
	s_mov_b32 m0, s41
	s_nop 0
	global_load_lds_dwordx4 v[218:219], off
	s_waitcnt vmcnt(8)
	s_waitcnt lgkmcnt(0)
	s_barrier
	s_setprio 1
	s_waitcnt lgkmcnt(0)
	v_mfma_f32_16x16x32_bf16 v[162:165], v[24:27], v[46:49], v[162:165]
	v_mfma_f32_16x16x32_bf16 v[158:161], v[38:41], v[46:49], v[158:161]
	v_mfma_f32_16x16x32_bf16 v[146:149], v[24:27], v[86:89], v[146:149]
	v_mfma_f32_16x16x32_bf16 v[142:145], v[38:41], v[86:89], v[142:145]
	v_mfma_f32_16x16x32_bf16 v[130:133], v[24:27], v[196:199], v[130:133]
	v_mfma_f32_16x16x32_bf16 v[126:129], v[38:41], v[196:199], v[126:129]
	v_mfma_f32_16x16x32_bf16 v[114:117], v[24:27], v[244:247], v[114:117]
	v_mfma_f32_16x16x32_bf16 v[110:113], v[38:41], v[244:247], v[110:113]
	v_mfma_f32_16x16x32_bf16 v[162:165], v[28:31], v[50:53], v[162:165]
	v_mfma_f32_16x16x32_bf16 v[158:161], v[42:45], v[50:53], v[158:161]
	v_mfma_f32_16x16x32_bf16 v[146:149], v[28:31], v[90:93], v[146:149]
	v_mfma_f32_16x16x32_bf16 v[142:145], v[42:45], v[90:93], v[142:145]
	v_mfma_f32_16x16x32_bf16 v[130:133], v[28:31], v[210:213], v[130:133]
	v_mfma_f32_16x16x32_bf16 v[126:129], v[42:45], v[210:213], v[126:129]
	v_mfma_f32_16x16x32_bf16 v[114:117], v[28:31], v[248:251], v[114:117]
	v_mfma_f32_16x16x32_bf16 v[110:113], v[42:45], v[248:251], v[110:113]
	s_setprio 0
	s_setprio 1
	v_mfma_f32_16x16x32_bf16 v[154:157], v[166:169], v[46:49], v[154:157]
	v_mfma_f32_16x16x32_bf16 v[46:49], v[174:177], v[46:49], v[150:153]
	v_mfma_f32_16x16x32_bf16 v[150:153], v[178:181], v[50:53], v[46:49]
	v_mfma_f32_16x16x32_bf16 v[46:49], v[166:169], v[86:89], v[138:141]
	v_mfma_f32_16x16x32_bf16 v[138:141], v[170:173], v[90:93], v[46:49]
	v_mfma_f32_16x16x32_bf16 v[46:49], v[174:177], v[86:89], v[134:137]
	v_mfma_f32_16x16x32_bf16 v[134:137], v[178:181], v[90:93], v[46:49]
	v_mfma_f32_16x16x32_bf16 v[46:49], v[166:169], v[196:199], v[122:125]
	v_mfma_f32_16x16x32_bf16 v[122:125], v[170:173], v[210:213], v[46:49]
	v_mfma_f32_16x16x32_bf16 v[46:49], v[174:177], v[196:199], v[118:121]
	v_mfma_f32_16x16x32_bf16 v[118:121], v[178:181], v[210:213], v[46:49]
	v_mfma_f32_16x16x32_bf16 v[46:49], v[166:169], v[244:247], v[106:109]
	v_mfma_f32_16x16x32_bf16 v[106:109], v[170:173], v[248:251], v[46:49]
	v_mfma_f32_16x16x32_bf16 v[46:49], v[174:177], v[244:247], v[102:105]
	v_mfma_f32_16x16x32_bf16 v[154:157], v[170:173], v[50:53], v[154:157]
	v_mfma_f32_16x16x32_bf16 v[102:105], v[178:181], v[248:251], v[46:49]
	s_setprio 0
	s_barrier
	s_add_i32 s0, s0, s95
	s_nop 2
	v_lshl_add_u64 v[46:47], v[202:203], 0, s[68:69]
	s_mov_b32 m0, s0
	ds_read_b128 v[86:89], v209 offset:49152
	ds_read_b128 v[196:199], v209 offset:50176
	ds_read_b128 v[210:213], v209 offset:51200
	ds_read_b128 v[244:247], v209 offset:52224
	ds_read_b128 v[248:251], v209 offset:53248
	ds_read_b128 v[228:231], v209 offset:54272
	ds_read_b128 v[232:235], v209 offset:55296
	ds_read_b128 v[218:221], v209 offset:56320
	global_load_lds_dwordx4 v[46:47], off
	s_add_i32 m0, s0, 0x2000
	s_add_u32 s34, s34, 0x40080
	v_lshl_add_u64 v[46:47], v[214:215], 0, s[68:69]
	s_addc_u32 s35, s35, 0
	s_add_i32 s0, s54, s95
	global_load_lds_dwordx4 v[46:47], off
	v_lshl_add_u64 v[46:47], s[34:35], 0, v[182:183]
	s_mov_b32 m0, s0
	s_nop 0
	global_load_lds_dwordx4 v[46:47], off
	v_lshl_add_u64 v[46:47], s[34:35], 0, v[34:35]
	s_add_i32 m0, s0, 0x2000
	s_nop 0
	global_load_lds_dwordx4 v[46:47], off
	v_lshl_add_u64 v[46:47], v[222:223], 0, s[68:69]
	s_mov_b32 m0, s43
	s_nop 0
	global_load_lds_dwordx4 v[46:47], off
	v_lshl_add_u64 v[46:47], v[236:237], 0, s[68:69]
	s_mov_b32 m0, s83
	s_nop 0
	global_load_lds_dwordx4 v[46:47], off
	s_waitcnt vmcnt(8)
	s_waitcnt lgkmcnt(0)
	s_barrier
	s_setprio 1
	s_waitcnt lgkmcnt(0)
	v_mfma_f32_16x16x32_bf16 v[46:49], v[24:27], v[86:89], v[98:101]
	v_mfma_f32_16x16x32_bf16 v[98:101], v[28:31], v[196:199], v[46:49]
	v_mfma_f32_16x16x32_bf16 v[46:49], v[38:41], v[86:89], v[94:97]
	v_mfma_f32_16x16x32_bf16 v[94:97], v[42:45], v[196:199], v[46:49]
	v_mfma_f32_16x16x32_bf16 v[46:49], v[24:27], v[210:213], v[82:85]
	v_mfma_f32_16x16x32_bf16 v[82:85], v[28:31], v[244:247], v[46:49]
	v_mfma_f32_16x16x32_bf16 v[46:49], v[38:41], v[210:213], v[78:81]
	v_mfma_f32_16x16x32_bf16 v[78:81], v[42:45], v[244:247], v[46:49]
	v_mfma_f32_16x16x32_bf16 v[46:49], v[24:27], v[248:251], v[66:69]
	v_mfma_f32_16x16x32_bf16 v[0:3], v[24:27], v[232:235], v[0:3]
	v_mfma_f32_16x16x32_bf16 v[66:69], v[28:31], v[228:231], v[46:49]
	v_mfma_f32_16x16x32_bf16 v[46:49], v[38:41], v[248:251], v[62:65]
	v_mfma_f32_16x16x32_bf16 v[50:53], v[28:31], v[218:221], v[0:3]
	v_mfma_f32_16x16x32_bf16 v[0:3], v[38:41], v[232:235], v[4:7]
	v_mfma_f32_16x16x32_bf16 v[62:65], v[42:45], v[228:231], v[46:49]
	v_mfma_f32_16x16x32_bf16 v[46:49], v[42:45], v[218:221], v[0:3]
	s_setprio 0
	s_setprio 1
	v_mfma_f32_16x16x32_bf16 v[0:3], v[166:169], v[86:89], v[8:11]
	v_mfma_f32_16x16x32_bf16 v[90:93], v[170:173], v[196:199], v[0:3]
	v_mfma_f32_16x16x32_bf16 v[0:3], v[174:177], v[86:89], v[12:15]
	v_mfma_f32_16x16x32_bf16 v[86:89], v[178:181], v[196:199], v[0:3]
	v_mfma_f32_16x16x32_bf16 v[0:3], v[166:169], v[210:213], v[74:77]
	v_mfma_f32_16x16x32_bf16 v[74:77], v[170:173], v[244:247], v[0:3]
	v_mfma_f32_16x16x32_bf16 v[0:3], v[174:177], v[210:213], v[70:73]
	v_mfma_f32_16x16x32_bf16 v[70:73], v[178:181], v[244:247], v[0:3]
	v_mfma_f32_16x16x32_bf16 v[0:3], v[166:169], v[248:251], v[58:61]
	v_mfma_f32_16x16x32_bf16 v[58:61], v[170:173], v[228:231], v[0:3]
	v_mfma_f32_16x16x32_bf16 v[0:3], v[174:177], v[248:251], v[54:57]
	v_mfma_f32_16x16x32_bf16 v[54:57], v[178:181], v[228:231], v[0:3]
	v_mfma_f32_16x16x32_bf16 v[0:3], v[166:169], v[232:235], v[16:19]
	v_mfma_f32_16x16x32_bf16 v[42:45], v[170:173], v[218:221], v[0:3]
	v_mfma_f32_16x16x32_bf16 v[0:3], v[174:177], v[232:235], v[20:23]
	v_mfma_f32_16x16x32_bf16 v[38:41], v[178:181], v[218:221], v[0:3]
	s_setprio 0
	s_barrier
	s_cmp_gt_u32 s89, 13
	s_mov_b32 s89, s92
	s_cbranch_scc1 .LBB0_343
	s_branch .LBB0_316

.LBB0_471:
	s_and_b32 s20, s12, 3
	s_add_i32 m0, s53, 0x18000
	v_lshl_add_u64 v[6:7], v[6:7], 0, s[68:69]
	s_lshl_b32 s63, s13, 6
	s_lshl_b32 s12, s13, 13
	s_lshl_b32 s18, s20, 12
	s_waitcnt vmcnt(2)
	s_barrier
	global_load_lds_dwordx4 v[6:7], off
	v_lshl_add_u64 v[4:5], v[4:5], 0, s[68:69]
	s_add_i32 m0, s53, 0x1a000
	s_add_i32 s64, s53, 0x8000
	s_add_i32 s65, s53, 0xa000
	global_load_lds_dwordx4 v[4:5], off
	v_lshl_add_u64 v[0:1], v[0:1], 0, s[68:69]
	s_mov_b32 m0, s64
	s_add_u32 s6, s8, 0x40080
	global_load_lds_dwordx4 v[0:1], off
	v_lshl_add_u64 v[0:1], v[2:3], 0, s[68:69]
	s_mov_b32 m0, s65
	s_addc_u32 s7, s9, 0
	global_load_lds_dwordx4 v[0:1], off
	s_add_i32 m0, s53, 0x1c000
	v_lshl_add_u64 v[0:1], s[6:7], 0, v[182:183]
	global_load_lds_dwordx4 v[0:1], off
	v_lshl_add_u64 v[0:1], s[6:7], 0, v[34:35]
	s_add_i32 m0, s53, 0x1e000
	v_and_b32_e32 v204, 15, v8
	global_load_lds_dwordx4 v[0:1], off
	v_bfe_u32 v1, v8, 4, 2
	v_lshlrev_b32_e32 v0, 4, v1
	v_lshlrev_b32_e32 v3, 2, v8
	v_lshl_or_b32 v2, v204, 6, v0
	v_and_b32_e32 v3, 32, v3
	s_cmpk_lt_u32 s0, 0x100
	v_bitop3_b32 v205, v2, s18, v3 bitop3:0xde
	s_cselect_b64 s[18:19], -1, 0
	s_bitcmp0_b32 s0, 6
	s_cselect_b64 s[6:7], -1, 0
	s_lshl_b32 s0, s13, 2
	v_bitop3_b32 v4, v2, s12, v3 bitop3:0xde
	s_or_b32 s12, s0, s20
	s_ashr_i32 s13, s12, 31
	s_lshl_b64 s[12:13], s[12:13], 13
	v_lshlrev_b32_e32 v2, 4, v204
	s_add_u32 s12, s54, s12
	v_lshl_or_b32 v32, v1, 8, v2
	s_addc_u32 s13, s87, s13
	v_lshl_add_u64 v[190:191], s[12:13], 0, v[32:33]
	v_readlane_b32 s12, v253, 42
	s_waitcnt vmcnt(6)
	v_readlane_b32 s13, v253, 43
	v_lshl_or_b32 v2, s20, 6, v0
	v_mov_b32_e32 v3, v33
	v_mov_b32_e32 v1, v33
	s_mov_b32 s72, s12
	v_readlane_b32 s12, v253, 46
	s_mov_b32 s70, 0
	v_or_b32_e32 v206, 16, v204
	v_or_b32_e32 v207, 32, v204
	v_or_b32_e32 v208, 48, v204
	v_lshl_add_u64 v[188:189], s[24:25], 0, v[2:3]
	v_lshl_add_u64 v[192:193], s[30:31], 0, v[0:1]
	v_lshl_add_u64 v[194:195], s[36:37], 0, v[0:1]
	v_add_u32_e32 v209, 0, v4
	s_mov_b32 s73, s12
	s_barrier
	v_readlane_b32 s13, v253, 47
	s_mov_b32 s100, 0
	s_branch .LBB0_474

.LBB0_473:
	s_andn2_b64 vcc, exec, s[8:9]
	s_cmp_lt_u32 s72, 16
	s_cselect_b32 s100, 16, 8
	s_mov_b32 s72, s22
	s_mov_b32 s73, s20
	s_mov_b64 s[8:9], s[38:39]
	s_mov_b64 s[10:11], s[36:37]
	s_cbranch_vccz .LBB0_541

.Lpeel_b:
	s_mov_b64 s[34:35], -1
	s_or_b32 s92, s76, 1
	s_lshl_b64 s[42:43], s[92:93], 7
	s_add_u32 s0, s10, s42
	s_addc_u32 s48, s11, s43
	s_add_i32 s92, s76, 2
	s_lshl_b64 s[46:47], s[92:93], 7
	s_add_u32 s49, s10, s46
	s_addc_u32 s54, s11, s47
	s_and_b64 s[42:43], s[34:35], exec
	s_cselect_b32 s43, s54, s21
	s_cselect_b32 s42, s49, s66
	s_add_u32 s46, s8, s46
	s_addc_u32 s47, s9, s47
	s_and_b64 s[34:35], s[34:35], exec
	s_cselect_b32 s35, s47, s23
	s_cselect_b32 s34, s46, s74
	s_add_i32 s49, 0, 0x10000
	s_add_i32 s54, 0, 0x14000
	v_add_u32_e32 v12, s49, v205
	v_add_u32_e32 v28, s54, v205
	ds_read_b128 v[0:3], v12
	ds_read_b128 v[4:7], v12 offset:1024
	ds_read_b128 v[8:11], v12 offset:2048
	ds_read_b128 v[12:15], v12 offset:3072
	ds_read_b128 v[16:19], v28
	ds_read_b128 v[20:23], v28 offset:1024
	ds_read_b128 v[24:27], v28 offset:2048
	ds_read_b128 v[28:31], v28 offset:3072
	s_add_u32 s46, s0, 0x40000
	s_addc_u32 s47, s48, 0
	v_lshl_add_u64 v[202:203], s[46:47], 0, v[184:185]
	s_add_i32 m0, s53, 0xc000
	ds_read_b128 v[166:169], v209
	ds_read_b128 v[170:173], v209 offset:1024
	ds_read_b128 v[174:177], v209 offset:2048
	ds_read_b128 v[178:181], v209 offset:3072
	ds_read_b128 v[196:199], v209 offset:4096
	ds_read_b128 v[210:213], v209 offset:5120
	ds_read_b128 v[218:221], v209 offset:6144
	ds_read_b128 v[228:231], v209 offset:7168
	global_load_lds_dwordx4 v[202:203], off
	v_lshl_add_u64 v[202:203], s[46:47], 0, v[186:187]
	s_add_i32 m0, s53, 0xe000
	s_nop 0
	global_load_lds_dwordx4 v[202:203], off
	s_cmp_eq_u32 s100, 16
	s_cbranch_scc1 .Lw16_b0
	s_cmp_eq_u32 s100, 8
	s_cbranch_scc1 .Lw8_b0
	s_waitcnt vmcnt(8)
	s_branch .Lwd_b0

.Lwd_b0:
	s_waitcnt lgkmcnt(0)
	s_barrier
	s_setprio 1
	s_waitcnt lgkmcnt(0)
	v_mfma_f32_16x16x32_bf16 v[162:165], v[0:3], v[166:169], 0
	v_mfma_f32_16x16x32_bf16 v[158:161], v[8:11], v[166:169], 0
	v_mfma_f32_16x16x32_bf16 v[146:149], v[0:3], v[174:177], 0
	v_mfma_f32_16x16x32_bf16 v[142:145], v[8:11], v[174:177], 0
	v_mfma_f32_16x16x32_bf16 v[130:133], v[0:3], v[196:199], 0
	v_mfma_f32_16x16x32_bf16 v[126:129], v[8:11], v[196:199], 0
	v_mfma_f32_16x16x32_bf16 v[114:117], v[0:3], v[218:221], 0
	v_mfma_f32_16x16x32_bf16 v[110:113], v[8:11], v[218:221], 0
	v_mfma_f32_16x16x32_bf16 v[162:165], v[4:7], v[170:173], v[162:165]
	v_mfma_f32_16x16x32_bf16 v[158:161], v[12:15], v[170:173], v[158:161]
	v_mfma_f32_16x16x32_bf16 v[146:149], v[4:7], v[178:181], v[146:149]
	v_mfma_f32_16x16x32_bf16 v[142:145], v[12:15], v[178:181], v[142:145]
	v_mfma_f32_16x16x32_bf16 v[130:133], v[4:7], v[210:213], v[130:133]
	v_mfma_f32_16x16x32_bf16 v[126:129], v[12:15], v[210:213], v[126:129]
	v_mfma_f32_16x16x32_bf16 v[114:117], v[4:7], v[228:231], v[114:117]
	v_mfma_f32_16x16x32_bf16 v[110:113], v[12:15], v[228:231], v[110:113]
	s_setprio 0
	s_setprio 1
	v_mfma_f32_16x16x32_bf16 v[154:157], v[16:19], v[166:169], 0
	v_mfma_f32_16x16x32_bf16 v[150:153], v[24:27], v[166:169], 0
	v_mfma_f32_16x16x32_bf16 v[138:141], v[16:19], v[174:177], 0
	v_mfma_f32_16x16x32_bf16 v[134:137], v[24:27], v[174:177], 0
	v_mfma_f32_16x16x32_bf16 v[122:125], v[16:19], v[196:199], 0
	v_mfma_f32_16x16x32_bf16 v[118:121], v[24:27], v[196:199], 0
	v_mfma_f32_16x16x32_bf16 v[106:109], v[16:19], v[218:221], 0
	v_mfma_f32_16x16x32_bf16 v[102:105], v[24:27], v[218:221], 0
	v_mfma_f32_16x16x32_bf16 v[154:157], v[20:23], v[170:173], v[154:157]
	v_mfma_f32_16x16x32_bf16 v[150:153], v[28:31], v[170:173], v[150:153]
	v_mfma_f32_16x16x32_bf16 v[138:141], v[20:23], v[178:181], v[138:141]
	v_mfma_f32_16x16x32_bf16 v[134:137], v[28:31], v[178:181], v[134:137]
	v_mfma_f32_16x16x32_bf16 v[122:125], v[20:23], v[210:213], v[122:125]
	v_mfma_f32_16x16x32_bf16 v[118:121], v[28:31], v[210:213], v[118:121]
	v_mfma_f32_16x16x32_bf16 v[106:109], v[20:23], v[228:231], v[106:109]
	v_mfma_f32_16x16x32_bf16 v[102:105], v[28:31], v[228:231], v[102:105]
	s_setprio 0
	s_barrier
	s_add_i32 s0, s49, s52
	v_lshl_add_u64 v[202:203], s[34:35], 0, v[182:183]
	s_mov_b32 m0, s0
	ds_read_b128 v[166:169], v209 offset:16384
	ds_read_b128 v[170:173], v209 offset:17408
	ds_read_b128 v[174:177], v209 offset:18432
	ds_read_b128 v[178:181], v209 offset:19456
	ds_read_b128 v[196:199], v209 offset:20480
	ds_read_b128 v[210:213], v209 offset:21504
	ds_read_b128 v[218:221], v209 offset:22528
	ds_read_b128 v[228:231], v209 offset:23552
	global_load_lds_dwordx4 v[202:203], off
	s_add_i32 m0, s0, 0x2000
	s_add_u32 s46, s34, 0x40000
	v_lshl_add_u64 v[214:215], s[34:35], 0, v[34:35]
	s_addc_u32 s47, s35, 0
	s_add_i32 s0, s54, s52
	global_load_lds_dwordx4 v[214:215], off
	v_lshl_add_u64 v[222:223], s[46:47], 0, v[182:183]
	s_mov_b32 m0, s0
	v_lshl_add_u64 v[236:237], s[42:43], 0, v[186:187]
	global_load_lds_dwordx4 v[222:223], off
	v_lshl_add_u64 v[222:223], s[46:47], 0, v[34:35]
	s_add_i32 m0, s0, 0x2000
	s_nop 0
	global_load_lds_dwordx4 v[222:223], off
	v_lshl_add_u64 v[222:223], s[42:43], 0, v[184:185]
	s_mov_b32 m0, s53
	s_nop 0
	global_load_lds_dwordx4 v[222:223], off
	s_mov_b32 m0, s56
	s_nop 0
	global_load_lds_dwordx4 v[236:237], off
	s_cmp_eq_u32 s100, 16
	s_cbranch_scc1 .Lw16_b1
	s_cmp_eq_u32 s100, 8
	s_cbranch_scc1 .Lw8_b1
	s_waitcnt vmcnt(8)
	s_branch .Lwd_b1

.Lwd_b1:
	s_waitcnt lgkmcnt(0)
	s_barrier
	s_setprio 1
	s_waitcnt lgkmcnt(0)
	v_mfma_f32_16x16x32_bf16 v[98:101], v[0:3], v[166:169], 0
	v_mfma_f32_16x16x32_bf16 v[94:97], v[8:11], v[166:169], 0
	v_mfma_f32_16x16x32_bf16 v[82:85], v[0:3], v[174:177], 0
	v_mfma_f32_16x16x32_bf16 v[78:81], v[8:11], v[174:177], 0
	v_mfma_f32_16x16x32_bf16 v[66:69], v[0:3], v[196:199], 0
	v_mfma_f32_16x16x32_bf16 v[62:65], v[8:11], v[196:199], 0
	v_mfma_f32_16x16x32_bf16 v[0:3], v[0:3], v[218:221], 0
	v_mfma_f32_16x16x32_bf16 v[98:101], v[4:7], v[170:173], v[98:101]
	v_mfma_f32_16x16x32_bf16 v[94:97], v[12:15], v[170:173], v[94:97]
	v_mfma_f32_16x16x32_bf16 v[82:85], v[4:7], v[178:181], v[82:85]
	v_mfma_f32_16x16x32_bf16 v[78:81], v[12:15], v[178:181], v[78:81]
	v_mfma_f32_16x16x32_bf16 v[66:69], v[4:7], v[210:213], v[66:69]
	v_mfma_f32_16x16x32_bf16 v[62:65], v[12:15], v[210:213], v[62:65]
	v_mfma_f32_16x16x32_bf16 v[0:3], v[4:7], v[228:231], v[0:3]
	v_mfma_f32_16x16x32_bf16 v[4:7], v[8:11], v[218:221], 0
	v_mfma_f32_16x16x32_bf16 v[4:7], v[12:15], v[228:231], v[4:7]
	s_setprio 0
	s_setprio 1
	v_mfma_f32_16x16x32_bf16 v[46:49], v[16:19], v[174:177], 0
	v_mfma_f32_16x16x32_bf16 v[74:77], v[20:23], v[178:181], v[46:49]
	v_mfma_f32_16x16x32_bf16 v[46:49], v[24:27], v[174:177], 0
	v_mfma_f32_16x16x32_bf16 v[70:73], v[28:31], v[178:181], v[46:49]
	v_mfma_f32_16x16x32_bf16 v[46:49], v[16:19], v[196:199], 0
	v_mfma_f32_16x16x32_bf16 v[8:11], v[16:19], v[166:169], 0
	v_mfma_f32_16x16x32_bf16 v[58:61], v[20:23], v[210:213], v[46:49]
	v_mfma_f32_16x16x32_bf16 v[46:49], v[24:27], v[196:199], 0
	v_mfma_f32_16x16x32_bf16 v[16:19], v[16:19], v[218:221], 0
	v_mfma_f32_16x16x32_bf16 v[8:11], v[20:23], v[170:173], v[8:11]
	v_mfma_f32_16x16x32_bf16 v[12:15], v[24:27], v[166:169], 0
	v_mfma_f32_16x16x32_bf16 v[54:57], v[28:31], v[210:213], v[46:49]
	v_mfma_f32_16x16x32_bf16 v[16:19], v[20:23], v[228:231], v[16:19]
	v_mfma_f32_16x16x32_bf16 v[20:23], v[24:27], v[218:221], 0
	v_mfma_f32_16x16x32_bf16 v[12:15], v[28:31], v[170:173], v[12:15]
	v_mfma_f32_16x16x32_bf16 v[20:23], v[28:31], v[228:231], v[20:23]
	s_setprio 0
	s_barrier
	s_add_i32 s0, 0, 0x18000
	v_add_u32_e32 v32, s0, v205
	s_add_i32 s46, 0, 0x1c000
	ds_read_b128 v[24:27], v32
	ds_read_b128 v[28:31], v32 offset:1024
	ds_read_b128 v[38:41], v32 offset:2048
	ds_read_b128 v[42:45], v32 offset:3072
	v_add_u32_e32 v32, s46, v205
	ds_read_b128 v[166:169], v32
	ds_read_b128 v[170:173], v32 offset:1024
	ds_read_b128 v[174:177], v32 offset:2048
	ds_read_b128 v[178:181], v32 offset:3072
	s_add_u32 s42, s42, 0x40000
	s_addc_u32 s43, s43, 0
	s_mov_b32 m0, s57
	v_lshl_add_u64 v[232:233], s[42:43], 0, v[184:185]
	ds_read_b128 v[46:49], v209 offset:32768
	ds_read_b128 v[50:53], v209 offset:33792
	ds_read_b128 v[86:89], v209 offset:34816
	ds_read_b128 v[90:93], v209 offset:35840
	ds_read_b128 v[196:199], v209 offset:36864
	ds_read_b128 v[210:213], v209 offset:37888
	ds_read_b128 v[218:221], v209 offset:38912
	ds_read_b128 v[228:231], v209 offset:39936
	global_load_lds_dwordx4 v[232:233], off
	v_lshl_add_u64 v[232:233], s[42:43], 0, v[186:187]
	s_mov_b32 m0, s62
	s_nop 0
	global_load_lds_dwordx4 v[232:233], off
	s_waitcnt vmcnt(8)
	s_waitcnt lgkmcnt(0)
	s_barrier
	s_setprio 1
	s_waitcnt lgkmcnt(0)
	v_mfma_f32_16x16x32_bf16 v[162:165], v[24:27], v[46:49], v[162:165]
	v_mfma_f32_16x16x32_bf16 v[158:161], v[38:41], v[46:49], v[158:161]
	v_mfma_f32_16x16x32_bf16 v[146:149], v[24:27], v[86:89], v[146:149]
	v_mfma_f32_16x16x32_bf16 v[142:145], v[38:41], v[86:89], v[142:145]
	v_mfma_f32_16x16x32_bf16 v[130:133], v[24:27], v[196:199], v[130:133]
	v_mfma_f32_16x16x32_bf16 v[126:129], v[38:41], v[196:199], v[126:129]
	v_mfma_f32_16x16x32_bf16 v[114:117], v[24:27], v[218:221], v[114:117]
	v_mfma_f32_16x16x32_bf16 v[110:113], v[38:41], v[218:221], v[110:113]
	v_mfma_f32_16x16x32_bf16 v[162:165], v[28:31], v[50:53], v[162:165]
	v_mfma_f32_16x16x32_bf16 v[158:161], v[42:45], v[50:53], v[158:161]
	v_mfma_f32_16x16x32_bf16 v[146:149], v[28:31], v[90:93], v[146:149]
	v_mfma_f32_16x16x32_bf16 v[142:145], v[42:45], v[90:93], v[142:145]
	v_mfma_f32_16x16x32_bf16 v[130:133], v[28:31], v[210:213], v[130:133]
	v_mfma_f32_16x16x32_bf16 v[126:129], v[42:45], v[210:213], v[126:129]
	v_mfma_f32_16x16x32_bf16 v[114:117], v[28:31], v[228:231], v[114:117]
	v_mfma_f32_16x16x32_bf16 v[110:113], v[42:45], v[228:231], v[110:113]
	s_setprio 0
	s_setprio 1
	v_mfma_f32_16x16x32_bf16 v[154:157], v[166:169], v[46:49], v[154:157]
	v_mfma_f32_16x16x32_bf16 v[46:49], v[174:177], v[46:49], v[150:153]
	v_mfma_f32_16x16x32_bf16 v[150:153], v[178:181], v[50:53], v[46:49]
	v_mfma_f32_16x16x32_bf16 v[46:49], v[166:169], v[86:89], v[138:141]
	v_mfma_f32_16x16x32_bf16 v[138:141], v[170:173], v[90:93], v[46:49]
	v_mfma_f32_16x16x32_bf16 v[46:49], v[174:177], v[86:89], v[134:137]
	v_mfma_f32_16x16x32_bf16 v[134:137], v[178:181], v[90:93], v[46:49]
	v_mfma_f32_16x16x32_bf16 v[46:49], v[166:169], v[196:199], v[122:125]
	v_mfma_f32_16x16x32_bf16 v[122:125], v[170:173], v[210:213], v[46:49]
	v_mfma_f32_16x16x32_bf16 v[46:49], v[174:177], v[196:199], v[118:121]
	v_mfma_f32_16x16x32_bf16 v[118:121], v[178:181], v[210:213], v[46:49]
	v_mfma_f32_16x16x32_bf16 v[46:49], v[166:169], v[218:221], v[106:109]
	v_mfma_f32_16x16x32_bf16 v[106:109], v[170:173], v[228:231], v[46:49]
	v_mfma_f32_16x16x32_bf16 v[46:49], v[174:177], v[218:221], v[102:105]
	v_mfma_f32_16x16x32_bf16 v[154:157], v[170:173], v[50:53], v[154:157]
	v_mfma_f32_16x16x32_bf16 v[102:105], v[178:181], v[228:231], v[46:49]
	s_setprio 0
	s_barrier
	s_add_i32 s0, s0, s52
	s_nop 2
	v_lshl_add_u64 v[46:47], v[202:203], 0, s[68:69]
	s_mov_b32 m0, s0
	ds_read_b128 v[86:89], v209 offset:49152
	ds_read_b128 v[196:199], v209 offset:50176
	ds_read_b128 v[210:213], v209 offset:51200
	ds_read_b128 v[218:221], v209 offset:52224
	ds_read_b128 v[228:231], v209 offset:53248
	ds_read_b128 v[232:235], v209 offset:54272
	ds_read_b128 v[244:247], v209 offset:55296
	ds_read_b128 v[248:251], v209 offset:56320
	global_load_lds_dwordx4 v[46:47], off
	s_add_i32 m0, s0, 0x2000
	s_add_u32 s34, s34, 0x40080
	v_lshl_add_u64 v[46:47], v[214:215], 0, s[68:69]
	s_addc_u32 s35, s35, 0
	s_add_i32 s0, s46, s52
	global_load_lds_dwordx4 v[46:47], off
	v_lshl_add_u64 v[46:47], s[34:35], 0, v[182:183]
	s_mov_b32 m0, s0
	s_nop 0
	global_load_lds_dwordx4 v[46:47], off
	v_lshl_add_u64 v[46:47], s[34:35], 0, v[34:35]
	s_add_i32 m0, s0, 0x2000
	s_nop 0
	global_load_lds_dwordx4 v[46:47], off
	v_lshl_add_u64 v[46:47], v[222:223], 0, s[68:69]
	s_mov_b32 m0, s64
	s_nop 0
	global_load_lds_dwordx4 v[46:47], off
	v_lshl_add_u64 v[46:47], v[236:237], 0, s[68:69]
	s_mov_b32 m0, s65
	s_nop 0
	global_load_lds_dwordx4 v[46:47], off
	s_waitcnt vmcnt(8)
	s_waitcnt lgkmcnt(0)
	s_barrier
	s_setprio 1
	s_waitcnt lgkmcnt(0)
	v_mfma_f32_16x16x32_bf16 v[46:49], v[24:27], v[86:89], v[98:101]
	v_mfma_f32_16x16x32_bf16 v[98:101], v[28:31], v[196:199], v[46:49]
	v_mfma_f32_16x16x32_bf16 v[46:49], v[38:41], v[86:89], v[94:97]
	v_mfma_f32_16x16x32_bf16 v[94:97], v[42:45], v[196:199], v[46:49]
	v_mfma_f32_16x16x32_bf16 v[46:49], v[24:27], v[210:213], v[82:85]
	v_mfma_f32_16x16x32_bf16 v[82:85], v[28:31], v[218:221], v[46:49]
	v_mfma_f32_16x16x32_bf16 v[46:49], v[38:41], v[210:213], v[78:81]
	v_mfma_f32_16x16x32_bf16 v[78:81], v[42:45], v[218:221], v[46:49]
	v_mfma_f32_16x16x32_bf16 v[46:49], v[24:27], v[228:231], v[66:69]
	v_mfma_f32_16x16x32_bf16 v[0:3], v[24:27], v[244:247], v[0:3]
	v_mfma_f32_16x16x32_bf16 v[66:69], v[28:31], v[232:235], v[46:49]
	v_mfma_f32_16x16x32_bf16 v[46:49], v[38:41], v[228:231], v[62:65]
	v_mfma_f32_16x16x32_bf16 v[50:53], v[28:31], v[248:251], v[0:3]
	v_mfma_f32_16x16x32_bf16 v[0:3], v[38:41], v[244:247], v[4:7]
	v_mfma_f32_16x16x32_bf16 v[62:65], v[42:45], v[232:235], v[46:49]
	v_mfma_f32_16x16x32_bf16 v[46:49], v[42:45], v[248:251], v[0:3]
	s_setprio 0
	s_setprio 1
	v_mfma_f32_16x16x32_bf16 v[0:3], v[166:169], v[86:89], v[8:11]
	v_mfma_f32_16x16x32_bf16 v[90:93], v[170:173], v[196:199], v[0:3]
	v_mfma_f32_16x16x32_bf16 v[0:3], v[174:177], v[86:89], v[12:15]
	v_mfma_f32_16x16x32_bf16 v[86:89], v[178:181], v[196:199], v[0:3]
	v_mfma_f32_16x16x32_bf16 v[0:3], v[166:169], v[210:213], v[74:77]
	v_mfma_f32_16x16x32_bf16 v[74:77], v[170:173], v[218:221], v[0:3]
	v_mfma_f32_16x16x32_bf16 v[0:3], v[174:177], v[210:213], v[70:73]
	v_mfma_f32_16x16x32_bf16 v[70:73], v[178:181], v[218:221], v[0:3]
	v_mfma_f32_16x16x32_bf16 v[0:3], v[166:169], v[228:231], v[58:61]
	v_mfma_f32_16x16x32_bf16 v[58:61], v[170:173], v[232:235], v[0:3]
	v_mfma_f32_16x16x32_bf16 v[0:3], v[174:177], v[228:231], v[54:57]
	v_mfma_f32_16x16x32_bf16 v[54:57], v[178:181], v[232:235], v[0:3]
	v_mfma_f32_16x16x32_bf16 v[0:3], v[166:169], v[244:247], v[16:19]
	v_mfma_f32_16x16x32_bf16 v[42:45], v[170:173], v[248:251], v[0:3]
	v_mfma_f32_16x16x32_bf16 v[0:3], v[174:177], v[244:247], v[20:23]
	v_mfma_f32_16x16x32_bf16 v[38:41], v[178:181], v[248:251], v[0:3]
	s_setprio 0
	s_barrier
	s_cmp_gt_u32 s76, 13
	s_mov_b32 s76, s92
	s_cbranch_scc1 .LBB0_515
	s_branch .LBB0_483
